# GRID_BAR(2) also group-local (P2 state scan and P3 mixers of one batch run on one XCC)
# speedup vs baseline: 1.0103x; 1.0023x over previous
; __device__ __forceinline__ unsigned xb_ld(unsigned* p)              { return __hip_atomic_load(p, __ATOMIC_RELAXED, __HIP_MEMORY_SCOPE_AGENT); }
; __device__ __forceinline__ unsigned xb_add(unsigned* p, unsigned v) { return __hip_atomic_fetch_add(p, v, __ATOMIC_RELAXED, __HIP_MEMORY_SCOPE_AGENT); }
; #define XB_SPIN(cond, bar) do { unsigned _sp = 0; while (cond) { __builtin_amdgcn_s_sleep(1); \
;     if ((++_sp & 255u) == 0u) { if (xb_ld(&(bar)[XB_TMO])) break; if (_sp > XB_SPIN_CAP) { atomicAdd(&(bar)[XB_TMO], 1u); break; } } } } while (0)
; __device__ __forceinline__ void xcd_barrier(const XcdBarrier& b) {
;     asm volatile("s_waitcnt vmcnt(0)" ::: "memory");
;     __syncthreads();
;     if (threadIdx.x == 0) {
;         unsigned* bar = b.bar;
;         __builtin_amdgcn_s_waitcnt(0);
;         unsigned nloc = b.st[0], nx = b.st[1];
;         if (nloc == 0u) { xcd_barrier_complete(bar, b.x, nloc, nx); b.st[0] = nloc; b.st[1] = nx; }
;         const unsigned old = xb_add(&bar[XB_XSUB(b.x)], 1u);
;         const unsigned gen = old / nloc;
;         if (old + 1u == (gen + 1u) * nloc) {
;             __builtin_amdgcn_fence(__ATOMIC_RELEASE, "agent");
;             asm volatile("s_waitcnt vmcnt(0)" ::: "memory");
;             const unsigned og = xb_add(&bar[XB_TOP], 1u);
;             const unsigned tg = og / nx;
;             if (og + 1u == (tg + 1u) * nx) xb_add(&bar[XB_TOPGEN], 1u);
;             else XB_SPIN(xb_ld(&bar[XB_TOPGEN]) == tg, bar);
;             __builtin_amdgcn_fence(__ATOMIC_ACQUIRE, "agent");
;             xb_add(&bar[XB_XGEN(b.x)], 1u);
;             asm volatile("s_waitcnt vmcnt(0)" ::: "memory");
;         } else {
;             XB_SPIN(xb_ld(&bar[XB_XGEN(b.x)]) == gen, bar);
;             __builtin_amdgcn_fence(__ATOMIC_ACQUIRE, "agent");
;             asm volatile("s_waitcnt vmcnt(0)" ::: "memory");
;         }
;     }
;     __syncthreads();
.LBB0_251:
	s_cmp_gt_i32 s71, 3
	s_cselect_b64 s[0:1], -1, 0
	s_and_b64 s[6:7], s[6:7], s[0:1]
	s_andn2_b64 vcc, exec, s[6:7]
	s_cbranch_vccnz .LBB0_305
	s_waitcnt vmcnt(0)
	s_waitcnt vmcnt(0)
	s_barrier
	s_and_saveexec_b64 s[6:7], s[96:97]
	s_cbranch_execz .LBB0_304
	s_cmp_eq_u32 s99, 1
	s_cbranch_scc0 .Lgb2_global
	s_and_b32 s100, s2, 7
	s_lshl_b32 s100, s100, 8
	s_add_u32 s100, s100, 0x2d800
	v_mov_b32_e32 v254, s100
	v_mov_b32_e32 v255, 1
	global_atomic_add v253, v254, v255, s[76:77] sc0
	s_waitcnt vmcnt(0)
	v_readfirstlane_b32 s100, v253
	s_lshr_b32 s98, s100, 5
	s_add_u32 s100, s100, 1
	s_and_b32 s100, s100, 31
	s_cmp_eq_u32 s100, 0
	s_cbranch_scc0 .Lgb2_spin
	global_atomic_add v254, v255, s[76:77] offset:2048
	s_branch .Lgb2_acq

; __device__ __forceinline__ unsigned xb_ld(unsigned* p)              { return __hip_atomic_load(p, __ATOMIC_RELAXED, __HIP_MEMORY_SCOPE_AGENT); }
; __device__ __forceinline__ void xcd_barrier_complete(unsigned* bar, unsigned x, unsigned& nloc, unsigned& nx) {
;     const unsigned G = gridDim.x * gridDim.y * gridDim.z;
;     unsigned sum, cnt, mine, sp = 0u;
;     for (;;) {
;         sum = 0u; cnt = 0u; mine = 0u;
; #pragma unroll
;         for (unsigned j = 0; j < 16; ++j) { const unsigned c = xb_ld(&bar[XB_XCNT(j)]); sum += c; cnt += (c > 0u) ? 1u : 0u; mine = (j == x) ? c : mine; }
;         if (sum == G) break;
; __device__ __forceinline__ void xcd_barrier(const XcdBarrier& b) {
;     ...
;         unsigned nloc = b.st[0], nx = b.st[1];
;         if (nloc == 0u) { xcd_barrier_complete(bar, b.x, nloc, nx); b.st[0] = nloc; b.st[1] = nx; }
.Lgb2_global:
	s_add_i32 s8, 0, 0x20fc0
	v_mov_b32_e32 v0, s8
	s_waitcnt vmcnt(0) expcnt(0) lgkmcnt(0)
	ds_read_b32 v2, v0
	s_add_i32 s8, 0, 0x20fc4
	v_mov_b32_e32 v0, s8
	ds_read_b32 v0, v0
	s_waitcnt lgkmcnt(1)
	v_cmp_ne_u32_e32 vcc, 0, v2
	s_cbranch_vccnz .LBB0_268
	v_readlane_b32 s8, v244, 4
	v_readlane_b32 s9, v244, 5
	v_readlane_b32 s10, v244, 6
	s_mul_i32 s33, s9, s10
	s_mul_i32 s33, s33, s8
	s_add_u32 s8, s76, 0x20200
	s_addc_u32 s9, s77, 0
	s_add_u32 s10, s76, 0x20400
	s_addc_u32 s11, s77, 0
	s_add_u32 s12, s76, 0x20500
	s_addc_u32 s13, s77, 0
	s_add_u32 s14, s76, 0x20600
	s_addc_u32 s15, s77, 0
	s_add_u32 s16, s76, 0x20700
	s_addc_u32 s17, s77, 0
	s_add_u32 s18, s76, 0x20800
	s_addc_u32 s19, s77, 0
	s_add_u32 s20, s76, 0x20900
	s_addc_u32 s21, s77, 0
	s_add_u32 s22, s76, 0x20a00
	s_addc_u32 s23, s77, 0
	s_add_u32 s24, s76, 0x20b00
	s_addc_u32 s25, s77, 0
	s_add_u32 s26, s76, 0x20c00
	s_addc_u32 s27, s77, 0
	s_add_u32 s28, s76, 0x20d00
	s_addc_u32 s29, s77, 0
	s_add_u32 s30, s76, 0x20e00
	s_addc_u32 s31, s77, 0
	s_add_u32 s34, s76, 0x20f00
	s_addc_u32 s35, s77, 0
	s_add_u32 s36, s76, 0x21000
	s_addc_u32 s37, s77, 0
	s_add_u32 s38, s76, 0x21100
	s_addc_u32 s39, s77, 0
	s_add_u32 s40, s76, 0x21200
	s_addc_u32 s41, s77, 0
	s_add_u32 s42, s76, 0x21300
	s_addc_u32 s43, s77, 0
	s_mov_b32 s50, 1
	v_mov_b32_e32 v16, 0
	s_branch .LBB0_256
